# P8 scan loop: removed 0+x adds from the sa dependency chain (instruction selection), on top of v37
# baseline (speedup 1.0000x reference)
; __device__ __forceinline__ float bf2f(bf16_t b) { return __uint_as_float(((unsigned)b) << 16); }
; template <int MODE>
; __device__ __forceinline__ void scan_item(const DArgs& a, LAS float* W  , int row0, int nsteps, int h, int lane, bool first_is_start, const float* shift_prev  ,
;                                           const float* S_init  , float* S_final  , float* Uout, float* Pout) {
;     ...
;     auto prep = [&](const ScanRaw& rw) -> Prep {
;         Prep o; const float zr = bf2f(rw.zr), zk = bf2f(rw.zk), zv = bf2f(rw.zv);
;         const float r = zr + (zr_p - zr) * k.mu_r, kx = zk + (zk_p - zk) * k.mu_k; o.v = zv + (zv_p - zv) * k.mu_v;
;         zr_p = zr; zk_p = zk; zv_p = zv;
;         o.dec = __expf(-0.60653066f * sigmoidf_(k.w0 + rw.lw));
;         const float ai = sigmoidf_(k.a0 + rw.la);
;         const float kkr = kx * k.kkc, ssq = wave_sum(kkr * kkr), kk = kkr * rsqrtf(fmaxf(ssq, 1e-24f));
;         o.kmod = kx * (1.f + (ai - 1.f) * k.kac); o.an = -kk; o.bn = kk * ai; o.r = r; o.lg = rw.lg; o.bin = r * o.kmod * k.rk; return o; };
;     auto post = [&](float y, float bin, float v, float lg, int row, bool doit) {
;         const float mean = wave_sum(y) * (1.f / 64.f), dy = y - mean, var = wave_sum(dy * dy) * (1.f / 64.f);
;         const float yn = dy * rsqrtf(var + 64e-5f) * k.lnw + k.lnb;
;         const float bonus = wave_sum(bin) * v;
;         if (doit) mix[(size_t)row * D + 1024 + c] = f2bf((yn + bonus) * lg); };
;     ScanRaw raw1 = scan_load<MODE == 1>(P, L, row0 + (nsteps > 1 ? 1 : 0), c);
;     Prep pv = prep(scan_load<MODE == 1>(P, L, row0, c));
;     float yp = 0.f, binp = 0.f, vp = 0.f, lgp = 0.f;
;     for (int t = 0; t < nsteps; ++t) {
;         const int row = row0 + t;
;         const ScanRaw raw2 = scan_load<MODE == 1>(P, L, row0 + (t + 2 < nsteps ? t + 2 : nsteps - 1), c);
;         W[lane] = pv.an; W[64 + lane] = pv.dec; W[128 + lane] = pv.bn; if constexpr (MODE != 2) { W[192 + lane] = pv.kmod; W[320 + lane] = pv.v; } if constexpr (MODE == 1) W[256 + lane] = pv.r;
;         const Prep pn = prep(raw1);
;         constexpr int NS = 2, PW = 8 / NS;
;         float sa[4];
; #pragma unroll
;         for (int q = 0; q < 4; ++q) sa[q] = 0.f;
; #pragma unroll
;         for (int hf = 0; hf < NS; ++hf) {
;             f32x2 av[PW];
; #pragma unroll
.LBB0_726:
	s_min_u32 s22, s24, 0x7d
	v_mov_b32_e32 v145, v90
	v_add_u32_e32 v90, s22, v129
	v_mov_b64_e32 v[104:105], v[110:111]
	v_mad_i64_i32 v[110:111], s[22:23], v90, s30, v[106:107]
	v_mov_b32_e32 v144, v77
	v_mov_b32_e32 v77, v138
	v_lshl_add_u64 v[116:117], v[110:111], 0, s[8:9]
	global_load_ushort v138, v[110:111], off offset:2048
	global_load_ushort v139, v[116:117], off offset:2048
	v_add_co_u32_e32 v110, vcc, s28, v110
	v_lshlrev_b32_e32 v95, 16, v135
	s_nop 0
	v_addc_co_u32_e32 v111, vcc, 0, v111, vcc
	global_load_ushort v143, v[110:111], off offset:2048
	v_mad_i64_i32 v[110:111], s[22:23], v90, s35, v[100:101]
	global_load_dword v140, v[110:111], off
	v_add_co_u32_e32 v110, vcc, s29, v110
	v_mov_b32_e32 v146, v133
	s_nop 0
	v_addc_co_u32_e32 v111, vcc, 0, v111, vcc
	global_load_dword v141, v[110:111], off offset:-4096
	global_load_dword v142, v[110:111], off
	ds_write2st64_b32 v118, v89, v131 offset0:32 offset1:33
	ds_write2st64_b32 v118, v103, v102 offset0:34 offset1:35
	ds_write2st64_b32 v118, v104, v105 offset0:36 offset1:37
	v_sub_f32_e32 v89, v115, v95
	v_fma_f32 v102, v96, v89, v95
	v_add_f32_e32 v89, v123, v137
	v_mul_f32_e32 v89, 0xbfb8aa3b, v89
	v_exp_f32_e32 v89, v89
	v_mov_b32_e32 v110, 0
	ds_read_b128 v[114:117], v119 offset:8192
	ds_read_b128 v[148:151], v119 offset:8208
	ds_read_b128 v[152:155], v119 offset:8224
	ds_read_b128 v[156:159], v119 offset:8240
	v_mul_f32_e32 v133, v126, v78
	v_add_f32_e32 v89, 1.0, v89
	v_rcp_f32_e32 v89, v89
	s_waitcnt lgkmcnt(3)
	v_pk_mul_f32 v[160:161], v[58:59], v[116:117]
	v_mul_f32_e32 v89, 0xbf1b4598, v89
	v_mul_f32_e32 v90, 0x3fb8aa3b, v89
	v_add_f32_e32 v89, v124, v136
	v_mul_f32_e32 v89, 0xbfb8aa3b, v89
	v_exp_f32_e32 v89, v89
	v_pk_mul_f32 v[136:137], v[66:67], v[116:117]
	v_pk_fma_f32 v[160:161], v[56:57], v[114:115], v[160:161]
	v_pk_fma_f32 v[136:137], v[64:65], v[114:115], v[136:137]
	v_add_f32_e32 v89, 1.0, v89
	v_rcp_f32_e32 v103, v89
	v_mul_f32_e32 v89, v125, v102
	v_mul_f32_e32 v104, v89, v89
	s_waitcnt lgkmcnt(2)
	v_pk_fma_f32 v[136:137], v[60:61], v[148:149], v[136:137]
	v_pk_fma_f32 v[160:161], v[52:53], v[148:149], v[160:161]
	v_mov_b32_dpp v110, v104 quad_perm:[1,0,3,2] row_mask:0xf bank_mask:0xf
	v_fmac_f32_e32 v110, v89, v89
	v_pk_fma_f32 v[136:137], v[62:63], v[150:151], v[136:137]
	v_exp_f32_e32 v131, v90
	v_add_f32_dpp v104, v110, v110 quad_perm:[2,3,0,1] row_mask:0xf bank_mask:0xf bound_ctrl:1
	v_pk_fma_f32 v[160:161], v[54:55], v[150:151], v[160:161]
	s_nop 0
	v_add_f32_dpp v104, v104, v104 row_half_mirror row_mask:0xf bank_mask:0xf bound_ctrl:1
	s_nop 1
	v_add_f32_dpp v104, v104, v104 row_mirror row_mask:0xf bank_mask:0xf bound_ctrl:1
	s_nop 0
	v_readlane_b32 s25, v104, 16
	v_readlane_b32 s33, v104, 48
	v_readlane_b32 s22, v104, 0
	v_readlane_b32 s23, v104, 32
	v_mov_b32_e32 v110, s25
	v_mov_b32_e32 v111, s33
	v_pk_add_f32 v[110:111], s[22:23], v[110:111]
	s_nop 0
	v_add_f32_e32 v104, v110, v111
	v_max_f32_e32 v104, 0x179abe15, v104
	v_rsq_f32_e32 v104, v104
	v_add_f32_e32 v110, -1.0, v103
	v_fma_f32 v110, v97, v110, 1.0
	v_mul_f32_e64 v89, v89, -v104
	v_xor_b32_e32 v111, 0x80000000, v89
	v_pk_mul_f32 v[102:103], v[102:103], v[110:111]
	v_pk_mul_f32 v[110:111], v[74:75], v[116:117]
	v_pk_mul_f32 v[116:117], v[46:47], v[116:117]
	v_pk_fma_f32 v[110:111], v[72:73], v[114:115], v[110:111]
	v_pk_fma_f32 v[114:115], v[44:45], v[114:115], v[116:117]
	s_waitcnt lgkmcnt(1)
	v_pk_mul_f32 v[116:117], v[42:43], v[154:155]
	v_pk_fma_f32 v[110:111], v[68:69], v[148:149], v[110:111]
	v_pk_fma_f32 v[116:117], v[40:41], v[152:153], v[116:117]
	v_pk_fma_f32 v[110:111], v[70:71], v[150:151], v[110:111]
	s_waitcnt lgkmcnt(0)
	v_pk_fma_f32 v[116:117], v[36:37], v[156:157], v[116:117]
	v_pk_fma_f32 v[114:115], v[48:49], v[148:149], v[114:115]
	v_pk_fma_f32 v[116:117], v[38:39], v[158:159], v[116:117]
	v_mov_b32_e32 v148, v110
	v_mov_b32_e32 v149, v116
	v_mov_b32_e32 v116, v111
	v_pk_add_f32 v[110:111], v[148:149], v[116:117]
	v_mov_b32_e32 v116, v136
	s_nop 0
	v_add_f32_e32 v78, v110, v111
	v_pk_mul_f32 v[110:111], v[34:35], v[154:155]
	v_mov_b32_e32 v90, v78
	v_pk_fma_f32 v[110:111], v[32:33], v[152:153], v[110:111]
	s_nop 0
	v_permlane16_swap_b32_e32 v78, v90
	v_pk_fma_f32 v[110:111], v[24:25], v[156:157], v[110:111]
	v_add_f32_e32 v78, v78, v90
	v_pk_fma_f32 v[110:111], v[26:27], v[158:159], v[110:111]
	v_mov_b32_e32 v90, v78
	v_mov_b32_e32 v117, v110
	v_mov_b32_e32 v110, v137
	v_pk_add_f32 v[110:111], v[116:117], v[110:111]
	v_pk_fma_f32 v[114:115], v[50:51], v[150:151], v[114:115]
	s_nop 0
	v_add_f32_e32 v104, v110, v111
	v_pk_mul_f32 v[110:111], v[22:23], v[154:155]
	v_mov_b32_e32 v116, v160
	v_pk_fma_f32 v[110:111], v[20:21], v[152:153], v[110:111]
	v_permlane32_swap_b32_e32 v78, v90
	v_pk_fma_f32 v[110:111], v[28:29], v[156:157], v[110:111]
	s_nop 0
	v_pk_fma_f32 v[110:111], v[30:31], v[158:159], v[110:111]
	s_nop 0
	v_mov_b32_e32 v117, v110
	v_mov_b32_e32 v110, v161
	v_pk_add_f32 v[110:111], v[116:117], v[110:111]
	v_mov_b32_e32 v116, v114
	v_add_f32_e32 v114, v78, v90
	v_mov_b32_e32 v78, v104
	s_nop 0
	s_nop 0
	v_permlane16_swap_b32_e32 v104, v78
	v_add_f32_e32 v135, v110, v111
	v_pk_mul_f32 v[110:111], v[18:19], v[154:155]
	v_add_f32_e32 v78, v104, v78
	v_pk_fma_f32 v[110:111], v[16:17], v[152:153], v[110:111]
	v_mov_b32_e32 v90, v78
	v_pk_fma_f32 v[110:111], v[12:13], v[156:157], v[110:111]
	s_nop 0
	v_permlane32_swap_b32_e32 v78, v90
	v_pk_fma_f32 v[110:111], v[14:15], v[158:159], v[110:111]
	v_add_f32_e32 v104, v78, v90
	v_mov_b32_e32 v78, v135
	v_mov_b32_e32 v117, v110
	v_mov_b32_e32 v110, v115
	v_permlane16_swap_b32_e32 v135, v78
	v_pk_add_f32 v[110:111], v[116:117], v[110:111]
	v_add_f32_e32 v78, v135, v78
	s_nop 0
	v_mov_b32_e32 v90, v78
	v_add_f32_e32 v110, v110, v111
	s_nop 0
	v_permlane32_swap_b32_e32 v78, v90
	v_add_f32_e32 v90, v78, v90
	v_mov_b32_e32 v78, v110
	s_nop 1
	v_permlane16_swap_b32_e32 v110, v78
	v_add_f32_e32 v78, v110, v78
	v_mov_b32_e32 v110, v78
	s_nop 1
	v_permlane32_swap_b32_e32 v78, v110
	v_and_b32_e32 v117, 0xffff0000, v134
	v_lshlrev_b32_e32 v116, 16, v134
	v_add_f32_e32 v78, v78, v110
	v_pk_add_f32 v[110:111], v[112:113], v[116:117] neg_lo:[0,1] neg_hi:[0,1]
	ds_read2_b32 v[112:113], v130 offset0:64 offset1:80
	ds_read2_b32 v[164:165], v130 offset0:96 offset1:112
	ds_read_b128 v[134:137], v119 offset:8448
	ds_read_b128 v[148:151], v119 offset:8464
	ds_read_b128 v[152:155], v119 offset:8480
	ds_read_b128 v[156:159], v119 offset:8496
	ds_read_b128 v[160:163], v119 offset:8704
	ds_read_b128 v[170:173], v119 offset:8720
	ds_read_b128 v[174:177], v119 offset:8736
	ds_read_b128 v[178:181], v119 offset:8752
	ds_read_b128 v[182:185], v119 offset:8960
	ds_read_b128 v[186:189], v119 offset:8976
	ds_read_b128 v[190:193], v119 offset:8992
	ds_read_b128 v[194:197], v119 offset:9008
	v_pk_fma_f32 v[110:111], v[98:99], v[110:111], v[116:117]
	s_waitcnt lgkmcnt(3)
; #define LAS __attribute__((address_space(3)))
; #define LDV(dst_, vec_) { _Pragma("unroll") for (int m = 0; m < 4; ++m) { const f32x4 t_ = *(const LAS f32x4*)(W + (vec_) * 64 + 16 * ib + 4 * m); dst_[2 * m] = (f32x2){t_.x, t_.y}; dst_[2 * m + 1] = (f32x2){t_.z, t_.w}; } }
; template <int MODE>
; __device__ __forceinline__ void scan_item(const DArgs& a, LAS float* W  , int row0, int nsteps, int h, int lane, bool first_is_start, const float* shift_prev  ,
;                                           const float* S_init  , float* S_final  , float* Uout, float* Pout) {
;     ...
;         float vq[4];
; #pragma unroll
;         for (int q = 0; q < 4; ++q) vq[q] = MODE == 2 ? 0.f : W[320 + il + 16 * q];
; #pragma unroll
;         for (int hf = 0; hf < NS; ++hf) {
;             f32x2 wv[PW], bv[PW], kv[PW];
; #pragma unroll
;             for (int m = 0; m < PW / 2; ++m) { const int o_ = 16 * ib + 2 * PW * hf + 4 * m; const f32x4 t0 = *(const LAS f32x4*)(W + 64 + o_), t1 = *(const LAS f32x4*)(W + 128 + o_), t2 = MODE == 2 ? t1 : *(const LAS f32x4*)(W + 192 + o_);
;                 wv[2 * m] = (f32x2){t0.x, t0.y}; wv[2 * m + 1] = (f32x2){t0.z, t0.w}; bv[2 * m] = (f32x2){t1.x, t1.y}; bv[2 * m + 1] = (f32x2){t1.z, t1.w}; kv[2 * m] = (f32x2){t2.x, t2.y}; kv[2 * m + 1] = (f32x2){t2.z, t2.w}; }
; #pragma unroll
;             for (int q = 0; q < 4; ++q) {
;                 const f32x2 sa2 = (f32x2){sa[q], sa[q]}, v2 = (f32x2){vq[q], vq[q]};
; #pragma unroll
;                 for (int p = 0; p < PW; ++p) { if constexpr (MODE == 2) S[q][PW * hf + p] = S[q][PW * hf + p] * wv[p] + sa2 * bv[p]; else S[q][PW * hf + p] = S[q][PW * hf + p] * wv[p] + (sa2 * bv[p] + v2 * kv[p]); }
;             }
;         }
;         if constexpr (MODE == 1) {
;             f32x2 rv[8];
;             LDV(rv, 4)
	v_pk_mul_f32 v[198:199], v[112:113], v[182:183] op_sel_hi:[0,1]
	v_pk_fma_f32 v[198:199], v[114:115], v[160:161], v[198:199] op_sel_hi:[0,1,1]
	v_pk_fma_f32 v[72:73], v[72:73], v[134:135], v[198:199]
	v_pk_mul_f32 v[198:199], v[112:113], v[184:185] op_sel_hi:[0,1]
	v_pk_fma_f32 v[198:199], v[114:115], v[162:163], v[198:199] op_sel_hi:[0,1,1]
	v_pk_fma_f32 v[74:75], v[74:75], v[136:137], v[198:199]
	s_waitcnt lgkmcnt(2)
	v_pk_mul_f32 v[198:199], v[112:113], v[186:187] op_sel_hi:[0,1]
	v_pk_fma_f32 v[198:199], v[114:115], v[170:171], v[198:199] op_sel_hi:[0,1,1]
	v_pk_fma_f32 v[68:69], v[68:69], v[148:149], v[198:199]
	v_pk_mul_f32 v[198:199], v[112:113], v[188:189] op_sel_hi:[0,1]
	v_pk_fma_f32 v[198:199], v[114:115], v[172:173], v[198:199] op_sel_hi:[0,1,1]
	v_pk_fma_f32 v[70:71], v[70:71], v[150:151], v[198:199]
	v_mov_b32_e32 v198, v113
	v_pk_mul_f32 v[200:201], v[198:199], v[182:183] op_sel_hi:[0,1]
	v_pk_fma_f32 v[200:201], v[104:105], v[160:161], v[200:201] op_sel_hi:[0,1,1]
	v_pk_fma_f32 v[64:65], v[64:65], v[134:135], v[200:201]
	v_pk_mul_f32 v[200:201], v[198:199], v[184:185] op_sel_hi:[0,1]
	v_pk_fma_f32 v[200:201], v[104:105], v[162:163], v[200:201] op_sel_hi:[0,1,1]
	v_pk_fma_f32 v[66:67], v[66:67], v[136:137], v[200:201]
	v_pk_mul_f32 v[200:201], v[198:199], v[186:187] op_sel_hi:[0,1]
	v_pk_fma_f32 v[200:201], v[104:105], v[170:171], v[200:201] op_sel_hi:[0,1,1]
	v_pk_fma_f32 v[60:61], v[60:61], v[148:149], v[200:201]
	v_pk_mul_f32 v[200:201], v[198:199], v[188:189] op_sel_hi:[0,1]
	v_pk_fma_f32 v[200:201], v[104:105], v[172:173], v[200:201] op_sel_hi:[0,1,1]
	v_pk_fma_f32 v[62:63], v[62:63], v[150:151], v[200:201]
	v_pk_mul_f32 v[200:201], v[164:165], v[182:183] op_sel_hi:[0,1]
	v_pk_fma_f32 v[200:201], v[90:91], v[160:161], v[200:201] op_sel_hi:[0,1,1]
	v_pk_fma_f32 v[56:57], v[56:57], v[134:135], v[200:201]
	v_pk_mul_f32 v[200:201], v[164:165], v[184:185] op_sel_hi:[0,1]
	v_pk_fma_f32 v[200:201], v[90:91], v[162:163], v[200:201] op_sel_hi:[0,1,1]
	v_pk_fma_f32 v[58:59], v[58:59], v[136:137], v[200:201]
	v_pk_mul_f32 v[200:201], v[164:165], v[186:187] op_sel_hi:[0,1]
	v_pk_fma_f32 v[200:201], v[90:91], v[170:171], v[200:201] op_sel_hi:[0,1,1]
	v_pk_fma_f32 v[52:53], v[52:53], v[148:149], v[200:201]
	v_pk_mul_f32 v[200:201], v[164:165], v[188:189] op_sel_hi:[0,1]
	v_pk_fma_f32 v[200:201], v[90:91], v[172:173], v[200:201] op_sel_hi:[0,1,1]
	v_pk_fma_f32 v[54:55], v[54:55], v[150:151], v[200:201]
	v_mov_b32_e32 v200, v165
	v_pk_mul_f32 v[182:183], v[200:201], v[182:183] op_sel_hi:[0,1]
	v_pk_fma_f32 v[160:161], v[78:79], v[160:161], v[182:183] op_sel_hi:[0,1,1]
	v_pk_fma_f32 v[44:45], v[44:45], v[134:135], v[160:161]
	v_pk_mul_f32 v[134:135], v[200:201], v[184:185] op_sel_hi:[0,1]
	v_pk_fma_f32 v[134:135], v[78:79], v[162:163], v[134:135] op_sel_hi:[0,1,1]
	v_pk_fma_f32 v[46:47], v[46:47], v[136:137], v[134:135]
	v_pk_mul_f32 v[134:135], v[200:201], v[186:187] op_sel_hi:[0,1]
	v_pk_fma_f32 v[134:135], v[78:79], v[170:171], v[134:135] op_sel_hi:[0,1,1]
	v_pk_fma_f32 v[48:49], v[48:49], v[148:149], v[134:135]
	v_pk_mul_f32 v[134:135], v[200:201], v[188:189] op_sel_hi:[0,1]
	v_pk_fma_f32 v[134:135], v[78:79], v[172:173], v[134:135] op_sel_hi:[0,1,1]
	v_pk_fma_f32 v[50:51], v[50:51], v[150:151], v[134:135]
	s_waitcnt lgkmcnt(1)
	v_pk_mul_f32 v[134:135], v[112:113], v[190:191] op_sel_hi:[0,1]
	v_pk_fma_f32 v[134:135], v[114:115], v[174:175], v[134:135] op_sel_hi:[0,1,1]
	v_pk_fma_f32 v[40:41], v[40:41], v[152:153], v[134:135]
	v_pk_mul_f32 v[134:135], v[112:113], v[192:193] op_sel_hi:[0,1]
	v_pk_fma_f32 v[134:135], v[114:115], v[176:177], v[134:135] op_sel_hi:[0,1,1]
	v_pk_fma_f32 v[42:43], v[42:43], v[154:155], v[134:135]
	s_waitcnt lgkmcnt(0)
	v_pk_mul_f32 v[134:135], v[112:113], v[194:195] op_sel_hi:[0,1]
	v_pk_mul_f32 v[112:113], v[112:113], v[196:197] op_sel_hi:[0,1]
	v_pk_fma_f32 v[112:113], v[114:115], v[180:181], v[112:113] op_sel_hi:[0,1,1]
	v_pk_fma_f32 v[38:39], v[38:39], v[158:159], v[112:113]
	v_pk_mul_f32 v[112:113], v[198:199], v[190:191] op_sel_hi:[0,1]
	v_pk_fma_f32 v[112:113], v[104:105], v[174:175], v[112:113] op_sel_hi:[0,1,1]
	v_pk_fma_f32 v[32:33], v[32:33], v[152:153], v[112:113]
	v_pk_mul_f32 v[112:113], v[198:199], v[192:193] op_sel_hi:[0,1]
	v_pk_fma_f32 v[112:113], v[104:105], v[176:177], v[112:113] op_sel_hi:[0,1,1]
	v_pk_fma_f32 v[34:35], v[34:35], v[154:155], v[112:113]
	v_pk_mul_f32 v[112:113], v[198:199], v[194:195] op_sel_hi:[0,1]
	v_pk_fma_f32 v[112:113], v[104:105], v[178:179], v[112:113] op_sel_hi:[0,1,1]
	v_pk_fma_f32 v[24:25], v[24:25], v[156:157], v[112:113]
	v_pk_mul_f32 v[112:113], v[198:199], v[196:197] op_sel_hi:[0,1]
	v_pk_fma_f32 v[112:113], v[104:105], v[180:181], v[112:113] op_sel_hi:[0,1,1]
	v_pk_fma_f32 v[26:27], v[26:27], v[158:159], v[112:113]
	v_pk_mul_f32 v[112:113], v[164:165], v[190:191] op_sel_hi:[0,1]
	v_pk_fma_f32 v[112:113], v[90:91], v[174:175], v[112:113] op_sel_hi:[0,1,1]
	v_pk_fma_f32 v[20:21], v[20:21], v[152:153], v[112:113]
	v_pk_mul_f32 v[112:113], v[164:165], v[192:193] op_sel_hi:[0,1]
	v_pk_fma_f32 v[112:113], v[90:91], v[176:177], v[112:113] op_sel_hi:[0,1,1]
	v_pk_fma_f32 v[22:23], v[22:23], v[154:155], v[112:113]
	v_pk_mul_f32 v[112:113], v[164:165], v[194:195] op_sel_hi:[0,1]
	v_pk_fma_f32 v[112:113], v[90:91], v[178:179], v[112:113] op_sel_hi:[0,1,1]
	v_pk_fma_f32 v[28:29], v[28:29], v[156:157], v[112:113]
	v_pk_mul_f32 v[112:113], v[164:165], v[196:197] op_sel_hi:[0,1]
	v_pk_fma_f32 v[112:113], v[90:91], v[180:181], v[112:113] op_sel_hi:[0,1,1]
	v_pk_fma_f32 v[30:31], v[30:31], v[158:159], v[112:113]
	v_pk_mul_f32 v[112:113], v[200:201], v[190:191] op_sel_hi:[0,1]
	v_pk_fma_f32 v[112:113], v[78:79], v[174:175], v[112:113] op_sel_hi:[0,1,1]
	v_pk_fma_f32 v[16:17], v[16:17], v[152:153], v[112:113]
	v_pk_mul_f32 v[112:113], v[200:201], v[192:193] op_sel_hi:[0,1]
	v_pk_fma_f32 v[112:113], v[78:79], v[176:177], v[112:113] op_sel_hi:[0,1,1]
	v_pk_fma_f32 v[18:19], v[18:19], v[154:155], v[112:113]
	v_pk_mul_f32 v[112:113], v[200:201], v[194:195] op_sel_hi:[0,1]
	v_pk_fma_f32 v[112:113], v[78:79], v[178:179], v[112:113] op_sel_hi:[0,1,1]
	v_pk_fma_f32 v[12:13], v[12:13], v[156:157], v[112:113]
	v_pk_mul_f32 v[112:113], v[200:201], v[196:197] op_sel_hi:[0,1]
	v_pk_fma_f32 v[134:135], v[114:115], v[178:179], v[134:135] op_sel_hi:[0,1,1]
	v_pk_fma_f32 v[112:113], v[78:79], v[180:181], v[112:113] op_sel_hi:[0,1,1]
	v_pk_fma_f32 v[36:37], v[36:37], v[156:157], v[134:135]
	v_pk_fma_f32 v[14:15], v[14:15], v[158:159], v[112:113]
	ds_read_b128 v[112:115], v119 offset:9216
	ds_read_b128 v[134:137], v119 offset:9232
	ds_read_b128 v[148:151], v119 offset:9248
	ds_read_b128 v[152:155], v119 offset:9264
	v_mul_f32_e32 v78, v110, v102
	s_waitcnt lgkmcnt(3)
; __device__ __forceinline__ bf16_t f2bf(float f) { return (bf16_t)(pk2(f, 0.f) & 0xffffu); }
; #define LDV(dst_, vec_) { _Pragma("unroll") for (int m = 0; m < 4; ++m) { const f32x4 t_ = *(const LAS f32x4*)(W + (vec_) * 64 + 16 * ib + 4 * m); dst_[2 * m] = (f32x2){t_.x, t_.y}; dst_[2 * m + 1] = (f32x2){t_.z, t_.w}; } }
; template <int MODE>
; __device__ __forceinline__ void scan_item(const DArgs& a, LAS float* W  , int row0, int nsteps, int h, int lane, bool first_is_start, const float* shift_prev  ,
;                                           const float* S_init  , float* S_final  , float* Uout, float* Pout) {
;     ...
;     auto post = [&](float y, float bin, float v, float lg, int row, bool doit) {
;         const float mean = wave_sum(y) * (1.f / 64.f), dy = y - mean, var = wave_sum(dy * dy) * (1.f / 64.f);
;         const float yn = dy * rsqrtf(var + 64e-5f) * k.lnw + k.lnb;
;         const float bonus = wave_sum(bin) * v;
;         if (doit) mix[(size_t)row * D + 1024 + c] = f2bf((yn + bonus) * lg); };
;     ...
;         if constexpr (MODE == 1) {
;             f32x2 rv[8];
;             LDV(rv, 4)
;             float yq[4];
; #pragma unroll
;             for (int q = 0; q < 4; ++q) { f32x2 d = S[q][0] * rv[0];
; #pragma unroll
;                 for (int p = 1; p < 8; ++p) d += S[q][p] * rv[p];
;                 yq[q] = d.x + d.y; }
;             const u32x2 s02 = __builtin_amdgcn_permlane32_swap(__float_as_uint(yq[0]), __float_as_uint(yq[2]), false, false);
;             const u32x2 s13 = __builtin_amdgcn_permlane32_swap(__float_as_uint(yq[1]), __float_as_uint(yq[3]), false, false);
;             const float r02 = __uint_as_float(s02.x) + __uint_as_float(s02.y), r13 = __uint_as_float(s13.x) + __uint_as_float(s13.y);
;             const u32x2 sy = __builtin_amdgcn_permlane16_swap(__float_as_uint(r02), __float_as_uint(r13), false, false);
;             const float y = __uint_as_float(sy.x) + __uint_as_float(sy.y);
;             post(yp, binp, vp, lgp, row - 1, t > 0);
;             yp = y; binp = pv.bin; vp = pv.v; lgp = pv.lg;
;         }
;         pv = pn; raw1 = raw2;
	v_pk_mul_f32 v[156:157], v[74:75], v[114:115]
	v_pk_mul_f32 v[158:159], v[66:67], v[114:115]
	v_pk_mul_f32 v[160:161], v[58:59], v[114:115]
	v_pk_mul_f32 v[114:115], v[46:47], v[114:115]
	v_pk_fma_f32 v[156:157], v[72:73], v[112:113], v[156:157]
	v_pk_fma_f32 v[158:159], v[64:65], v[112:113], v[158:159]
	v_pk_fma_f32 v[160:161], v[56:57], v[112:113], v[160:161]
	v_pk_fma_f32 v[112:113], v[44:45], v[112:113], v[114:115]
	s_waitcnt lgkmcnt(2)
	v_pk_fma_f32 v[156:157], v[68:69], v[134:135], v[156:157]
	v_pk_fma_f32 v[158:159], v[60:61], v[134:135], v[158:159]
	v_pk_fma_f32 v[160:161], v[52:53], v[134:135], v[160:161]
	v_pk_fma_f32 v[112:113], v[48:49], v[134:135], v[112:113]
	v_pk_fma_f32 v[156:157], v[70:71], v[136:137], v[156:157]
	v_pk_fma_f32 v[158:159], v[62:63], v[136:137], v[158:159]
	v_pk_fma_f32 v[160:161], v[54:55], v[136:137], v[160:161]
	v_pk_fma_f32 v[112:113], v[50:51], v[136:137], v[112:113]
	s_waitcnt lgkmcnt(1)
	v_pk_fma_f32 v[156:157], v[40:41], v[148:149], v[156:157]
	v_pk_fma_f32 v[158:159], v[32:33], v[148:149], v[158:159]
	v_pk_fma_f32 v[160:161], v[20:21], v[148:149], v[160:161]
	v_pk_fma_f32 v[112:113], v[16:17], v[148:149], v[112:113]
	v_pk_fma_f32 v[156:157], v[42:43], v[150:151], v[156:157]
	v_pk_fma_f32 v[158:159], v[34:35], v[150:151], v[158:159]
	v_pk_fma_f32 v[160:161], v[22:23], v[150:151], v[160:161]
	v_pk_fma_f32 v[112:113], v[18:19], v[150:151], v[112:113]
	s_waitcnt lgkmcnt(0)
	v_pk_fma_f32 v[156:157], v[36:37], v[152:153], v[156:157]
	v_pk_fma_f32 v[158:159], v[24:25], v[152:153], v[158:159]
	v_pk_fma_f32 v[160:161], v[28:29], v[152:153], v[160:161]
	v_pk_fma_f32 v[112:113], v[12:13], v[152:153], v[112:113]
	v_pk_fma_f32 v[156:157], v[38:39], v[154:155], v[156:157]
	v_pk_fma_f32 v[158:159], v[26:27], v[154:155], v[158:159]
	v_pk_fma_f32 v[160:161], v[30:31], v[154:155], v[160:161]
	v_pk_fma_f32 v[112:113], v[14:15], v[154:155], v[112:113]
	v_pk_add_f32 v[156:157], v[156:157], v[156:157] op_sel:[0,1] op_sel_hi:[1,0]
	v_pk_add_f32 v[158:159], v[158:159], v[158:159] op_sel:[0,1] op_sel_hi:[1,0]
	v_pk_add_f32 v[160:161], v[160:161], v[160:161] op_sel:[0,1] op_sel_hi:[1,0]
	v_pk_add_f32 v[112:113], v[112:113], v[112:113] op_sel:[0,1] op_sel_hi:[1,0]
	s_nop 0
	v_permlane32_swap_b32_e32 v156, v160
	v_permlane32_swap_b32_e32 v158, v112
	v_add_f32_e32 v90, v156, v160
	v_add_f32_e32 v104, v158, v112
	s_nop 1
	v_permlane16_swap_b32_e32 v90, v104
	v_add_f32_e32 v90, v90, v104
	s_nop 0
	v_add_f32_dpp v104, v145, v145 quad_perm:[1,0,3,2] row_mask:0xf bank_mask:0xf bound_ctrl:1
	s_waitcnt vmcnt(1)
	v_mov_b32_e32 v136, v141
	v_mov_b32_e32 v137, v140
	v_add_f32_dpp v104, v104, v104 quad_perm:[2,3,0,1] row_mask:0xf bank_mask:0xf bound_ctrl:1
	s_nop 1
	v_add_f32_dpp v104, v104, v104 row_half_mirror row_mask:0xf bank_mask:0xf bound_ctrl:1
	s_nop 1
	v_add_f32_dpp v104, v104, v104 row_mirror row_mask:0xf bank_mask:0xf bound_ctrl:1
	s_nop 0
	v_readlane_b32 s25, v104, 16
	v_readlane_b32 s33, v104, 48
	v_readlane_b32 s22, v104, 0
	v_readlane_b32 s23, v104, 32
	v_mov_b32_e32 v112, s25
	v_mov_b32_e32 v113, s33
	v_pk_add_f32 v[112:113], s[22:23], v[112:113]
	s_nop 0
	v_add_f32_e32 v104, v112, v113
	v_fmac_f32_e32 v145, 0xbc800000, v104
	v_mul_f32_e32 v104, v145, v145
	v_mov_b32_e32 v112, 0
	s_nop 1
	v_mov_b32_dpp v112, v104 quad_perm:[1,0,3,2] row_mask:0xf bank_mask:0xf
	v_fmac_f32_e32 v112, v145, v145
	s_nop 1
	v_add_f32_dpp v104, v112, v112 quad_perm:[2,3,0,1] row_mask:0xf bank_mask:0xf bound_ctrl:1
	v_add_u32_e32 v112, s24, v128
	s_add_i32 s24, s24, 1
	v_add_f32_dpp v104, v104, v104 row_half_mirror row_mask:0xf bank_mask:0xf bound_ctrl:1
	s_cmpk_lg_i32 s24, 0x80
	s_nop 0
	v_add_f32_dpp v104, v104, v104 row_mirror row_mask:0xf bank_mask:0xf bound_ctrl:1
	s_nop 0
	v_readlane_b32 s22, v104, 0
	v_readlane_b32 s25, v104, 16
	v_readlane_b32 s23, v104, 32
	v_readlane_b32 s33, v104, 48
	v_add_f32_dpp v104, v146, v146 quad_perm:[1,0,3,2] row_mask:0xf bank_mask:0xf bound_ctrl:1
	v_mov_b32_e32 v134, s25
	v_mov_b32_e32 v135, s33
	v_add_f32_dpp v104, v104, v104 quad_perm:[2,3,0,1] row_mask:0xf bank_mask:0xf bound_ctrl:1
	v_pk_add_f32 v[134:135], s[22:23], v[134:135]
	s_nop 0
	v_add_f32_dpp v104, v104, v104 row_half_mirror row_mask:0xf bank_mask:0xf bound_ctrl:1
	s_nop 1
	v_add_f32_dpp v104, v104, v104 row_mirror row_mask:0xf bank_mask:0xf bound_ctrl:1
	s_nop 0
	v_readlane_b32 s40, v104, 0
	v_readlane_b32 s39, v104, 16
	v_readlane_b32 s41, v104, 32
	v_readlane_b32 s42, v104, 48
	v_add_f32_e32 v104, v134, v135
	v_fmamk_f32 v104, v104, 0x3c800000, v121
	v_cmp_gt_f32_e32 vcc, s37, v104
	v_mul_f32_e32 v113, 0x4b800000, v104
	v_mov_b32_e32 v114, s39
	v_cndmask_b32_e32 v104, v104, v113, vcc
	v_rsq_f32_e32 v104, v104
	v_mov_b32_e32 v115, s42
	v_pk_add_f32 v[114:115], s[40:41], v[114:115]
	v_perm_b32 v134, v143, v138, s36
	v_mul_f32_e32 v113, 0x45800000, v104
	v_cndmask_b32_e32 v104, v104, v113, vcc
	v_mul_f32_e32 v104, v145, v104
	v_pk_add_f32 v[114:115], v[114:115], v[114:115] op_sel:[0,1] op_sel_hi:[1,0]
	v_ashrrev_i32_e32 v113, 31, v112
	v_mov_b32_e32 v115, v104
	v_pk_mul_f32 v[114:115], v[92:93], v[114:115]
	v_lshlrev_b64 v[112:113], 12, v[112:113]
	v_add_f32_e32 v92, v122, v115
	v_add_f32_e32 v92, v114, v92
	v_mul_f32_e32 v92, v144, v92
	v_cvt_pk_bf16_f32 v92, v92, v79
	v_lshl_add_u64 v[112:113], v[108:109], 0, v[112:113]
	global_store_short v[112:113], v92, off offset:2048
	v_mov_b32_e32 v138, v87
	v_mov_b32_e32 v92, v105
	s_waitcnt vmcnt(1)
	v_mov_b32_e32 v87, v142
	v_mov_b32_e32 v135, v139
	v_mov_b32_e32 v115, v95
	v_mov_b64_e32 v[112:113], v[116:117]
	s_cbranch_scc1 .LBB0_726
; __device__ __forceinline__ bf16_t f2bf(float f) { return (bf16_t)(pk2(f, 0.f) & 0xffffu); }
; template <int MODE>
; __device__ __forceinline__ void scan_item(const DArgs& a, LAS float* W  , int row0, int nsteps, int h, int lane, bool first_is_start, const float* shift_prev  ,
;                                           const float* S_init  , float* S_final  , float* Uout, float* Pout) {
;     ...
;     auto post = [&](float y, float bin, float v, float lg, int row, bool doit) {
;         const float mean = wave_sum(y) * (1.f / 64.f), dy = y - mean, var = wave_sum(dy * dy) * (1.f / 64.f);
;         const float yn = dy * rsqrtf(var + 64e-5f) * k.lnw + k.lnb;
;         const float bonus = wave_sum(bin) * v;
;         if (doit) mix[(size_t)row * D + 1024 + c] = f2bf((yn + bonus) * lg); };
;     ...
;     if constexpr (MODE == 1) post(yp, binp, vp, lgp, row0 + nsteps - 1, true);
	v_add_f32_dpp v13, v90, v90 quad_perm:[1,0,3,2] row_mask:0xf bank_mask:0xf bound_ctrl:1
	v_mov_b32_e32 v92, v105
	v_or_b32_e32 v12, 0x7f, v127
	v_add_f32_dpp v13, v13, v13 quad_perm:[2,3,0,1] row_mask:0xf bank_mask:0xf bound_ctrl:1
	v_add_u32_e32 v76, s26, v76
	v_mov_b32_e32 v95, v79
	v_add_f32_dpp v13, v13, v13 row_half_mirror row_mask:0xf bank_mask:0xf bound_ctrl:1
	s_nop 1
	v_add_f32_dpp v13, v13, v13 row_mirror row_mask:0xf bank_mask:0xf bound_ctrl:1
	s_nop 0
	v_readlane_b32 s24, v13, 16
	v_readlane_b32 s25, v13, 48
	v_readlane_b32 s22, v13, 0
	v_readlane_b32 s23, v13, 32
	v_mov_b32_e32 v14, s24
	v_mov_b32_e32 v15, s25
	v_pk_add_f32 v[14:15], s[22:23], v[14:15]
	s_nop 0
	v_add_f32_e32 v13, v14, v15
	v_fmac_f32_e32 v90, 0xbc800000, v13
	v_mul_f32_e32 v13, v90, v90
	v_mov_b32_e32 v14, v79
	s_nop 1
	v_mov_b32_dpp v14, v13 quad_perm:[1,0,3,2] row_mask:0xf bank_mask:0xf
	v_fmac_f32_e32 v14, v90, v90
	s_nop 1
	v_add_f32_dpp v13, v14, v14 quad_perm:[2,3,0,1] row_mask:0xf bank_mask:0xf bound_ctrl:1
	s_nop 1
	v_add_f32_dpp v13, v13, v13 row_half_mirror row_mask:0xf bank_mask:0xf bound_ctrl:1
	s_nop 1
	v_add_f32_dpp v13, v13, v13 row_mirror row_mask:0xf bank_mask:0xf bound_ctrl:1
	s_nop 0
	v_readlane_b32 s22, v13, 0
	v_readlane_b32 s33, v13, 16
	v_readlane_b32 s23, v13, 32
	v_readlane_b32 s39, v13, 48
	v_add_f32_dpp v13, v133, v133 quad_perm:[1,0,3,2] row_mask:0xf bank_mask:0xf bound_ctrl:1
	v_mov_b32_e32 v14, s33
	v_mov_b32_e32 v15, s39
	v_add_f32_dpp v13, v13, v13 quad_perm:[2,3,0,1] row_mask:0xf bank_mask:0xf bound_ctrl:1
	v_pk_add_f32 v[14:15], s[22:23], v[14:15]
	s_nop 0
	v_add_f32_dpp v13, v13, v13 row_half_mirror row_mask:0xf bank_mask:0xf bound_ctrl:1
	s_nop 1
	v_add_f32_dpp v13, v13, v13 row_mirror row_mask:0xf bank_mask:0xf bound_ctrl:1
	s_nop 0
	v_readlane_b32 s24, v13, 0
	v_readlane_b32 s40, v13, 16
	v_readlane_b32 s25, v13, 32
	v_readlane_b32 s41, v13, 48
	v_add_f32_e32 v13, v14, v15
	v_fmamk_f32 v13, v13, 0x3c800000, v121
	v_mul_f32_e32 v14, 0x4b800000, v13
	v_cmp_gt_f32_e32 vcc, s37, v13
	v_mov_b32_e32 v15, s41
	s_nop 0
	v_cndmask_b32_e32 v13, v13, v14, vcc
	v_rsq_f32_e32 v13, v13
	v_mov_b32_e32 v14, s40
	v_pk_add_f32 v[14:15], s[24:25], v[14:15]
	v_mul_f32_e32 v16, 0x45800000, v13
	v_cndmask_b32_e32 v13, v13, v16, vcc
	v_mul_f32_e32 v13, v90, v13
	v_pk_add_f32 v[14:15], v[14:15], v[14:15] op_sel:[0,1] op_sel_hi:[1,0]
	v_cmp_lt_i32_e32 vcc, s38, v76
	v_mov_b32_e32 v15, v13
	v_pk_mul_f32 v[14:15], v[92:93], v[14:15]
	s_or_b64 s[6:7], vcc, s[6:7]
	v_add_f32_e32 v13, v122, v15
	v_add_f32_e32 v13, v14, v13
	v_mul_f32_e32 v13, v77, v13
	v_cvt_pk_bf16_f32 v14, v13, v79
	v_ashrrev_i32_e32 v13, 31, v12
	v_lshlrev_b64 v[12:13], 12, v[12:13]
	v_lshl_add_u64 v[12:13], s[20:21], 0, v[12:13]
	v_lshl_add_u64 v[12:13], v[12:13], 0, v[94:95]
	global_store_short v[12:13], v14, off offset:2048
	s_andn2_b64 exec, exec, s[6:7]
	s_cbranch_execnz .LBB0_723
